# attention: LDS-DMA pieces interleaved into QK MFMA chain (unconditional) + softmax max/alpha prefix (21 instr) hoisted before first PV MFMA to cover V tr-read latency
# speedup vs baseline: 1.0270x; 1.0163x over previous
; #define LAS __attribute__((address_space(3)))
; DI void attn_stage(const bf16_t* kbase, const bf16_t* vbase, unsigned koff, unsigned voff, LAS unsigned char* ldsbuf, int wid) {
; #pragma unroll
;     for (int i = 0; i < 2; ++i) {
;         const char* src = (const char*)kbase + (size_t)(i * 128) * 2;
;         __builtin_amdgcn_global_load_lds((const unsigned*)(src + koff), (LAS unsigned*)(ldsbuf + (wid + 8 * i) * 1024), 16, 0, 0);
;     }
; #pragma unroll
;     for (int i = 0; i < 2; ++i) {
;         const char* src = (const char*)vbase + (size_t)(16 * i * 2048) * 2;
;         __builtin_amdgcn_global_load_lds((const unsigned*)(src + voff), (LAS unsigned*)(ldsbuf + 16384 + (wid + 8 * i) * 1024), 16, 0, 0);
;     }
; }
; DI void phase_attn(int wid0, const Params& p, int L, unsigned char* lds, bool dry) {
;     ...
;             asm volatile("s_waitcnt vmcnt(0) lgkmcnt(0)" ::: "memory"); __builtin_amdgcn_s_barrier(); asm volatile("" ::: "memory");
;             if (t + 1 < ntiles) attn_stage(kh_ + (size_t)(b * 4096 + 32 * t) * 2048, vh_ + (size_t)(b * 4096 + 32 * t) * 2048, koff, voff, ldsl + 65536 + ((t + 1) & 1) * 32768, wid);
;             const int kpos0 = (t == 0) ? 0 : 16 + 32 * (t - 1);
;             if (kpos0 <= wq0 + 31) {
;                 const unsigned char* Ks = lds + 65536 + (t & 1) * 32768 + psub * 8192;
;                 f32x16 p0, p0b;
; #pragma unroll
;                 for (int r = 0; r < 16; ++r) { p0[r] = 0.f; p0b[r] = 0.f; }
;                 int swz = (r32 & 6) << 4, kro = r32 * 256 + ((hi ^ (r32 & 1)) << 4); asm volatile("" : "+v"(swz), "+v"(kro));
; #pragma unroll
;                 for (int d0 = 0; d0 < 8; d0 += 2) {
;                     const bf16x8 b0 = *(const bf16x8*)(Ks + kro + ((d0 * 32) ^ swz));
;                     const bf16x8 qf = *(const bf16x8*)(qlds + d0 * 1024);
;                     const bf16x8 b1 = *(const bf16x8*)(Ks + kro + (((d0 + 1) * 32) ^ swz));
;                     const bf16x8 qg = *(const bf16x8*)(qlds + (d0 + 1) * 1024);
;                     p0 = MFMA32(b0, qf, p0);
;                     p0b = MFMA32(b1, qg, p0b);
;                     if (d0 == 2) __builtin_amdgcn_sched_barrier(0);
;                 }
; #pragma unroll
;                 for (int r = 0; r < 16; ++r) p0[r] += p0b[r];
;                 __builtin_amdgcn_sched_barrier(0);
.LBB0_99:
	s_waitcnt vmcnt(0) lgkmcnt(0)
	s_barrier
	s_max_i32 s48, s7, 0
	s_cmp_gt_i32 s48, s38
	s_cbranch_scc1 .Lattn_skip0
	ds_read_b128 v[216:219], v188
	ds_read_b128 v[220:223], v177
	ds_read_b128 v[236:239], v209
	ds_read_b128 v[240:243], v210
	s_waitcnt lgkmcnt(2)
	v_mfma_f32_32x32x16_bf16 v[140:155], v[216:219], v[248:251], 0
	s_add_i32 m0, s4, 0x8000
	v_mfma_f32_32x32x16_bf16 v[140:155], v[220:223], v[252:255], v[140:155]
	global_load_lds_dwordx4 v131, s[88:89]
	ds_read_b128 v[216:219], v211
	ds_read_b128 v[220:223], v215
	s_waitcnt lgkmcnt(2)
	v_mfma_f32_32x32x16_bf16 v[140:155], v[236:239], v[200:203], v[140:155]
	s_add_i32 m0, s4, 0xa000
	v_mfma_f32_32x32x16_bf16 v[140:155], v[240:243], v[204:207], v[140:155]
	global_load_lds_dwordx4 v131, s[90:91]
	v_add_u32_e32 v131, 0x20000, v131
	ds_read_b128 v[236:239], v224
	ds_read_b128 v[240:243], v225
	s_waitcnt lgkmcnt(2)
	v_mfma_f32_32x32x16_bf16 v[140:155], v[216:219], v[164:167], v[140:155]
	s_add_i32 m0, s96, 0x4000
	v_mfma_f32_32x32x16_bf16 v[140:155], v[220:223], v[168:171], v[140:155]
	global_load_lds_dwordx4 v208, s[92:93]
	s_waitcnt lgkmcnt(0)
	v_mfma_f32_32x32x16_bf16 v[140:155], v[236:239], v[172:175], v[140:155]
	s_add_i32 m0, s96, 0x6000
	v_mfma_f32_32x32x16_bf16 v[140:155], v[240:243], v[232:235], v[140:155]
	global_load_lds_dwordx4 v208, s[94:95]
	v_add_u32_e32 v208, 0x20000, v208
	s_cmpk_gt_i32 s39, 0x7f
	s_cbranch_scc0 .Lattn_near0
	s_cmp_lg_u32 s67, 1
	s_cbranch_scc1 .Lattn_far0

; DI void phase_attn(int wid0, const Params& p, int L, unsigned char* lds, bool dry) {
;     ...
;                 float pmax = p0[0];
; #pragma unroll
;                 for (int r = 1; r < 16; ++r) pmax = fmaxf(pmax, p0[r]);
;                 { auto rr = __builtin_amdgcn_permlane32_swap(__float_as_uint(pmax), __float_as_uint(pmax), false, false); pmax = fmaxf(__uint_as_float(rr[0]), __uint_as_float(rr[1])); }
;                 float mn, alpha;
;                 if (__all(pmax - m_reg <= ATT_THR2)) { mn = m_reg; alpha = 1.f; }
;                 else { mn = fmaxf(m_reg, pmax); alpha = __builtin_amdgcn_exp2f(m_reg - mn); m_reg = mn; }
;                 float ps = 0.f;
; #pragma unroll
;                 for (int r = 0; r < 16; ++r) { p0[r] = __builtin_amdgcn_exp2f(p0[r] - mn); ps += p0[r]; }
;                 { auto rr = __builtin_amdgcn_permlane32_swap(__float_as_uint(ps), __float_as_uint(ps), false, false); ps = __uint_as_float(rr[0]) + __uint_as_float(rr[1]); }
;                 l_reg = l_reg * alpha + ps;
;                 __builtin_amdgcn_sched_barrier(0);
;                 bf16x8 pa0, pa1;
;     ...
;                 PK4(p0, 0, pa0); PK4(p0, 8, pa1);
;     ...
;                 __builtin_amdgcn_sched_barrier(0);
;                 if (__any(alpha < 1.f)) {
;                     if (hi == 0) al_l[r32] = alpha;
;                     asm volatile("s_waitcnt lgkmcnt(0)" ::: "memory");
;                     float ar[16];
; #pragma unroll
;                     for (int r = 0; r < 16; ++r) ar[r] = al_l[crow(r, hi)];
; #pragma unroll
;                     for (int d = 0; d < 8; ++d)
; #pragma unroll
;                         for (int r = 0; r < 16; ++r) o[d][r] *= ar[r];
;                 }
;                 __builtin_amdgcn_sched_barrier(0);
;                 LAS unsigned char* vbp = ldsl + 65536 + (t & 1) * 32768 + 16384 + v_rd_base(lane);
;                 __builtin_amdgcn_s_setprio(1);
;     ...
;                 {
;                     s16x4 a0, a1, a2, a3, b0_, b1_, b2_, b3_;
;                     PV_RD(0, a0, a1, a2, a3); SB();
;                     PV_RD(1, b0_, b1_, b2_, b3_); SB(); PV_MM(0, a0, a1, a2, a3); SB();
;                     PV_RD(2, a0, a1, a2, a3); SB(); PV_MM(1, b0_, b1_, b2_, b3_); SB();
;                     PV_RD(3, b0_, b1_, b2_, b3_); SB(); PV_MM(2, a0, a1, a2, a3); SB();
;                     PV_RD(4, a0, a1, a2, a3); SB(); PV_MM(3, b0_, b1_, b2_, b3_); SB();
.Lattn_region0:
	ds_read_b64_tr_b16 v[216:217], v212 offset:49152
	ds_read_b64_tr_b16 v[218:219], v212 offset:53248
	ds_read_b64_tr_b16 v[220:221], v212 offset:57344
	ds_read_b64_tr_b16 v[222:223], v212 offset:61440
	ds_read_b64_tr_b16 v[236:237], v212 offset:49664
	ds_read_b64_tr_b16 v[238:239], v212 offset:53760
	ds_read_b64_tr_b16 v[240:241], v212 offset:57856
	ds_read_b64_tr_b16 v[242:243], v212 offset:61952
	v_max3_f32 v226, v140, v141, v142
	v_max3_f32 v226, v226, v143, v144
	v_max3_f32 v226, v226, v145, v146
	v_max3_f32 v226, v226, v147, v148
	v_max3_f32 v226, v226, v149, v150
	v_max3_f32 v226, v226, v151, v152
	v_max3_f32 v226, v226, v153, v154
	v_max_f32_e32 v226, v226, v155
	v_mov_b32_e32 v227, v226
	s_nop 1
	v_permlane32_swap_b32_e32 v226, v227
	v_max_f32_e32 v226, v226, v227
	v_fma_f32 v226, v226, s82, v231
	v_sub_f32_e32 v227, v226, v213
	v_cmp_ge_f32_e32 vcc, s97, v227
	s_cmp_eq_u64 vcc, exec
	v_max_f32_e32 v226, v213, v226
	s_cselect_b64 vcc, -1, 0
	v_sub_f32_e32 v227, v213, v226
	v_cndmask_b32_e32 v213, v226, v213, vcc
	v_sub_f32_e32 v230, v231, v213
	s_waitcnt lgkmcnt(4)
	v_mfma_f32_32x32x16_bf16 v[114:129], v[132:135], v[216:219], v[114:129]
	v_mfma_f32_32x32x16_bf16 v[114:129], v[136:139], v[220:223], v[114:129]
	v_fma_f32 v140, v140, s82, v230
	v_exp_f32_e32 v140, v140
	v_fma_f32 v141, v141, s82, v230
	v_exp_f32_e32 v141, v141
	ds_read_b64_tr_b16 v[216:217], v212 offset:50176
	ds_read_b64_tr_b16 v[218:219], v212 offset:54272
	ds_read_b64_tr_b16 v[220:221], v212 offset:58368
	ds_read_b64_tr_b16 v[222:223], v212 offset:62464
	s_waitcnt lgkmcnt(4)
	v_mfma_f32_32x32x16_bf16 v[98:113], v[132:135], v[236:239], v[98:113]
	v_fma_f32 v142, v142, s82, v230
	v_exp_f32_e32 v142, v142
	v_add_f32_e32 v226, v140, v141
	v_fma_f32 v143, v143, s82, v230
	v_exp_f32_e32 v143, v143
	v_mfma_f32_32x32x16_bf16 v[98:113], v[136:139], v[240:243], v[98:113]
	v_add_f32_e32 v226, v226, v142
	v_fma_f32 v144, v144, s82, v230
	v_exp_f32_e32 v144, v144
	v_add_f32_e32 v226, v226, v143
	v_fma_f32 v145, v145, s82, v230
	ds_read_b64_tr_b16 v[236:237], v212 offset:50688
	ds_read_b64_tr_b16 v[238:239], v212 offset:54784
	ds_read_b64_tr_b16 v[240:241], v212 offset:58880
	ds_read_b64_tr_b16 v[242:243], v212 offset:62976
	s_waitcnt lgkmcnt(4)
	v_mfma_f32_32x32x16_bf16 v[82:97], v[132:135], v[216:219], v[82:97]
	v_exp_f32_e32 v145, v145
	v_add_f32_e32 v226, v226, v144
	v_fma_f32 v146, v146, s82, v230
	v_exp_f32_e32 v146, v146
	v_mfma_f32_32x32x16_bf16 v[82:97], v[136:139], v[220:223], v[82:97]
	v_add_f32_e32 v226, v226, v145
	v_fma_f32 v147, v147, s82, v230
	v_exp_f32_e32 v147, v147
	v_add_f32_e32 v226, v226, v146
	v_fma_f32 v148, v148, s82, v230
	ds_read_b64_tr_b16 v[216:217], v212 offset:51200
	ds_read_b64_tr_b16 v[218:219], v212 offset:55296
	ds_read_b64_tr_b16 v[220:221], v212 offset:59392
	ds_read_b64_tr_b16 v[222:223], v212 offset:63488
	s_waitcnt lgkmcnt(4)
	v_mfma_f32_32x32x16_bf16 v[66:81], v[132:135], v[236:239], v[66:81]
	v_exp_f32_e32 v148, v148
	v_add_f32_e32 v226, v226, v147
	v_fma_f32 v149, v149, s82, v230
	v_exp_f32_e32 v149, v149
	v_mfma_f32_32x32x16_bf16 v[66:81], v[136:139], v[240:243], v[66:81]
	v_add_f32_e32 v226, v226, v148
	v_fma_f32 v150, v150, s82, v230
	v_exp_f32_e32 v150, v150
	v_add_f32_e32 v226, v226, v149
	ds_read_b64_tr_b16 v[236:237], v212 offset:51712
	ds_read_b64_tr_b16 v[238:239], v212 offset:55808
	ds_read_b64_tr_b16 v[240:241], v212 offset:59904
	ds_read_b64_tr_b16 v[242:243], v212 offset:64000
	s_waitcnt lgkmcnt(4)
	v_mfma_f32_32x32x16_bf16 v[50:65], v[132:135], v[216:219], v[50:65]
	v_fma_f32 v151, v151, s82, v230
	v_exp_f32_e32 v151, v151
	v_add_f32_e32 v226, v226, v150
	v_fma_f32 v152, v152, s82, v230
	v_mfma_f32_32x32x16_bf16 v[50:65], v[136:139], v[220:223], v[50:65]
	v_exp_f32_e32 v152, v152
	v_add_f32_e32 v226, v226, v151
	v_fma_f32 v153, v153, s82, v230
	v_exp_f32_e32 v153, v153
	ds_read_b64_tr_b16 v[216:217], v212 offset:52224
	ds_read_b64_tr_b16 v[218:219], v212 offset:56320
	ds_read_b64_tr_b16 v[220:221], v212 offset:60416
	ds_read_b64_tr_b16 v[222:223], v212 offset:64512
	s_waitcnt lgkmcnt(4)
	v_mfma_f32_32x32x16_bf16 v[34:49], v[132:135], v[236:239], v[34:49]
	v_add_f32_e32 v226, v226, v152
	v_fma_f32 v154, v154, s82, v230
	v_exp_f32_e32 v154, v154
	v_add_f32_e32 v226, v226, v153
	v_mfma_f32_32x32x16_bf16 v[34:49], v[136:139], v[240:243], v[34:49]
	v_fma_f32 v155, v155, s82, v230
	v_exp_f32_e32 v155, v155
	v_add_f32_e32 v226, v226, v154
	v_exp_f32_e32 v227, v227
	ds_read_b64_tr_b16 v[236:237], v212 offset:52736
	ds_read_b64_tr_b16 v[238:239], v212 offset:56832
	ds_read_b64_tr_b16 v[240:241], v212 offset:60928
	ds_read_b64_tr_b16 v[242:243], v212 offset:65024
	s_waitcnt lgkmcnt(4)
	v_mfma_f32_32x32x16_bf16 v[18:33], v[132:135], v[216:219], v[18:33]
	v_add_f32_e32 v228, v226, v155
	v_cndmask_b32_e64 v227, v227, 1.0, vcc
	v_mov_b32_e32 v229, v228
	v_cvt_pk_bf16_f32 v156, v140, v141
	v_cvt_pk_bf16_f32 v157, v142, v143
	v_mfma_f32_32x32x16_bf16 v[18:33], v[136:139], v[220:223], v[18:33]
	v_cvt_pk_bf16_f32 v158, v144, v145
	v_cvt_pk_bf16_f32 v159, v146, v147
	v_cvt_pk_bf16_f32 v160, v148, v149
	v_cvt_pk_bf16_f32 v161, v150, v151
	v_cvt_pk_bf16_f32 v162, v152, v153
	s_waitcnt lgkmcnt(0)
	v_mfma_f32_32x32x16_bf16 v[2:17], v[132:135], v[236:239], v[2:17]
	v_cvt_pk_bf16_f32 v163, v154, v155
	v_permlane32_swap_b32_e32 v228, v229
	v_permlane32_swap_b32_e32 v156, v158
	v_permlane32_swap_b32_e32 v157, v159
	v_mfma_f32_32x32x16_bf16 v[2:17], v[136:139], v[240:243], v[2:17]
	v_permlane32_swap_b32_e32 v160, v162
	v_permlane32_swap_b32_e32 v161, v163
	v_add_f32_e32 v228, v228, v229
	v_fma_f32 v130, v130, v227, v228
	s_cbranch_vccnz .Lattn_norescale0
; DI int crow(int r, int hi) { return (r & 3) + 8 * (r >> 2) + 4 * hi; }
; DI void phase_attn(int wid0, const Params& p, int L, unsigned char* lds, bool dry) {
;     ...
;                 if (__any(alpha < 1.f)) {
;                     if (hi == 0) al_l[r32] = alpha;
;                     asm volatile("s_waitcnt lgkmcnt(0)" ::: "memory");
;                     float ar[16];
; #pragma unroll
;                     for (int r = 0; r < 16; ++r) ar[r] = al_l[crow(r, hi)];
; #pragma unroll
;                     for (int d = 0; d < 8; ++d)
; #pragma unroll
;                         for (int r = 0; r < 16; ++r) o[d][r] *= ar[r];
;                 }
	s_and_saveexec_b64 s[80:81], s[8:9]
	ds_write_b32 v196, v227 offset:128
	s_or_b64 exec, exec, s[80:81]
	s_waitcnt lgkmcnt(0)
	ds_read_b128 v[152:155], v214 offset:224
	ds_read_b128 v[148:151], v214 offset:192
	ds_read_b128 v[144:147], v214 offset:160
	ds_read_b128 v[140:143], v214 offset:128
	s_waitcnt lgkmcnt(0)
	v_pk_mul_f32 v[126:127], v[126:127], v[152:153]
	v_pk_mul_f32 v[122:123], v[122:123], v[148:149]
	v_pk_mul_f32 v[118:119], v[118:119], v[144:145]
	v_pk_mul_f32 v[128:129], v[128:129], v[154:155]
	v_pk_mul_f32 v[124:125], v[124:125], v[150:151]
	v_pk_mul_f32 v[120:121], v[120:121], v[146:147]
	v_pk_mul_f32 v[116:117], v[116:117], v[142:143]
	v_pk_mul_f32 v[114:115], v[114:115], v[140:141]
	v_pk_mul_f32 v[110:111], v[110:111], v[152:153]
	v_pk_mul_f32 v[106:107], v[106:107], v[148:149]
	v_pk_mul_f32 v[102:103], v[102:103], v[144:145]
	v_pk_mul_f32 v[112:113], v[112:113], v[154:155]
	v_pk_mul_f32 v[108:109], v[108:109], v[150:151]
	v_pk_mul_f32 v[104:105], v[104:105], v[146:147]
	v_pk_mul_f32 v[100:101], v[100:101], v[142:143]
	v_pk_mul_f32 v[98:99], v[98:99], v[140:141]
	v_pk_mul_f32 v[94:95], v[94:95], v[152:153]
	v_pk_mul_f32 v[90:91], v[90:91], v[148:149]
	v_pk_mul_f32 v[86:87], v[86:87], v[144:145]
	v_pk_mul_f32 v[96:97], v[96:97], v[154:155]
	v_pk_mul_f32 v[92:93], v[92:93], v[150:151]
	v_pk_mul_f32 v[88:89], v[88:89], v[146:147]
	v_pk_mul_f32 v[84:85], v[84:85], v[142:143]
	v_pk_mul_f32 v[82:83], v[82:83], v[140:141]
	v_pk_mul_f32 v[78:79], v[78:79], v[152:153]
	v_pk_mul_f32 v[74:75], v[74:75], v[148:149]
	v_pk_mul_f32 v[70:71], v[70:71], v[144:145]
	v_pk_mul_f32 v[80:81], v[80:81], v[154:155]
	v_pk_mul_f32 v[76:77], v[76:77], v[150:151]
	v_pk_mul_f32 v[72:73], v[72:73], v[146:147]
	v_pk_mul_f32 v[68:69], v[68:69], v[142:143]
	v_pk_mul_f32 v[66:67], v[66:67], v[140:141]
	v_pk_mul_f32 v[62:63], v[62:63], v[152:153]
	v_pk_mul_f32 v[58:59], v[58:59], v[148:149]
	v_pk_mul_f32 v[54:55], v[54:55], v[144:145]
	v_pk_mul_f32 v[64:65], v[64:65], v[154:155]
	v_pk_mul_f32 v[60:61], v[60:61], v[150:151]
	v_pk_mul_f32 v[56:57], v[56:57], v[146:147]
	v_pk_mul_f32 v[52:53], v[52:53], v[142:143]
	v_pk_mul_f32 v[50:51], v[50:51], v[140:141]
	v_pk_mul_f32 v[46:47], v[46:47], v[152:153]
	v_pk_mul_f32 v[42:43], v[42:43], v[148:149]
	v_pk_mul_f32 v[38:39], v[38:39], v[144:145]
	v_pk_mul_f32 v[48:49], v[48:49], v[154:155]
	v_pk_mul_f32 v[44:45], v[44:45], v[150:151]
	v_pk_mul_f32 v[40:41], v[40:41], v[146:147]
	v_pk_mul_f32 v[36:37], v[36:37], v[142:143]
	v_pk_mul_f32 v[34:35], v[34:35], v[140:141]
	v_pk_mul_f32 v[30:31], v[30:31], v[152:153]
	v_pk_mul_f32 v[26:27], v[26:27], v[148:149]
	v_pk_mul_f32 v[22:23], v[22:23], v[144:145]
	v_pk_mul_f32 v[32:33], v[32:33], v[154:155]
	v_pk_mul_f32 v[28:29], v[28:29], v[150:151]
	v_pk_mul_f32 v[24:25], v[24:25], v[146:147]
	v_pk_mul_f32 v[20:21], v[20:21], v[142:143]
	v_pk_mul_f32 v[18:19], v[18:19], v[140:141]
	v_pk_mul_f32 v[14:15], v[14:15], v[152:153]
	v_pk_mul_f32 v[10:11], v[10:11], v[148:149]
	v_pk_mul_f32 v[6:7], v[6:7], v[144:145]
	v_pk_mul_f32 v[16:17], v[16:17], v[154:155]
	v_pk_mul_f32 v[12:13], v[12:13], v[150:151]
	v_pk_mul_f32 v[8:9], v[8:9], v[146:147]
	v_pk_mul_f32 v[4:5], v[4:5], v[142:143]
	v_pk_mul_f32 v[2:3], v[2:3], v[140:141]

; #define LAS __attribute__((address_space(3)))
; DI void attn_stage(const bf16_t* kbase, const bf16_t* vbase, unsigned koff, unsigned voff, LAS unsigned char* ldsbuf, int wid) {
; #pragma unroll
;     for (int i = 0; i < 2; ++i) {
;         const char* src = (const char*)kbase + (size_t)(i * 128) * 2;
;         __builtin_amdgcn_global_load_lds((const unsigned*)(src + koff), (LAS unsigned*)(ldsbuf + (wid + 8 * i) * 1024), 16, 0, 0);
;     }
; #pragma unroll
;     for (int i = 0; i < 2; ++i) {
;         const char* src = (const char*)vbase + (size_t)(16 * i * 2048) * 2;
;         __builtin_amdgcn_global_load_lds((const unsigned*)(src + voff), (LAS unsigned*)(ldsbuf + 16384 + (wid + 8 * i) * 1024), 16, 0, 0);
;     }
; }
; DI void phase_attn(int wid0, const Params& p, int L, unsigned char* lds, bool dry) {
;     ...
;             asm volatile("s_waitcnt vmcnt(0) lgkmcnt(0)" ::: "memory"); __builtin_amdgcn_s_barrier(); asm volatile("" ::: "memory");
;             if (t + 1 < ntiles) attn_stage(kh_ + (size_t)(b * 4096 + 32 * t) * 2048, vh_ + (size_t)(b * 4096 + 32 * t) * 2048, koff, voff, ldsl + 65536 + ((t + 1) & 1) * 32768, wid);
;             const int kpos0 = (t == 0) ? 0 : 16 + 32 * (t - 1);
;             if (kpos0 <= wq0 + 31) {
;                 const unsigned char* Ks = lds + 65536 + (t & 1) * 32768 + psub * 8192;
;                 f32x16 p0, p0b;
; #pragma unroll
;                 for (int r = 0; r < 16; ++r) { p0[r] = 0.f; p0b[r] = 0.f; }
;                 int swz = (r32 & 6) << 4, kro = r32 * 256 + ((hi ^ (r32 & 1)) << 4); asm volatile("" : "+v"(swz), "+v"(kro));
; #pragma unroll
;                 for (int d0 = 0; d0 < 8; d0 += 2) {
;                     const bf16x8 b0 = *(const bf16x8*)(Ks + kro + ((d0 * 32) ^ swz));
;                     const bf16x8 qf = *(const bf16x8*)(qlds + d0 * 1024);
;                     const bf16x8 b1 = *(const bf16x8*)(Ks + kro + (((d0 + 1) * 32) ^ swz));
;                     const bf16x8 qg = *(const bf16x8*)(qlds + (d0 + 1) * 1024);
;                     p0 = MFMA32(b0, qf, p0);
;                     p0b = MFMA32(b1, qg, p0b);
;                     if (d0 == 2) __builtin_amdgcn_sched_barrier(0);
;                 }
; #pragma unroll
;                 for (int r = 0; r < 16; ++r) p0[r] += p0b[r];
;                 __builtin_amdgcn_sched_barrier(0);
.Lattn_top1:
	s_waitcnt vmcnt(0) lgkmcnt(0)
	s_barrier
	s_max_i32 s48, s7, 0
	s_cmp_gt_i32 s48, s38
	s_cbranch_scc1 .Lattn_skip1
	ds_read_b128 v[216:219], v188 offset:32768
	ds_read_b128 v[220:223], v177 offset:32768
	ds_read_b128 v[236:239], v209 offset:32768
	ds_read_b128 v[240:243], v210 offset:32768
	s_waitcnt lgkmcnt(2)
	v_mfma_f32_32x32x16_bf16 v[140:155], v[216:219], v[248:251], 0
	s_add_i32 m0, s4, 0x0
	v_mfma_f32_32x32x16_bf16 v[140:155], v[220:223], v[252:255], v[140:155]
	global_load_lds_dwordx4 v131, s[88:89]
	ds_read_b128 v[216:219], v211 offset:32768
	ds_read_b128 v[220:223], v215 offset:32768
	s_waitcnt lgkmcnt(2)
	v_mfma_f32_32x32x16_bf16 v[140:155], v[236:239], v[200:203], v[140:155]
	s_add_i32 m0, s4, 0x2000
	v_mfma_f32_32x32x16_bf16 v[140:155], v[240:243], v[204:207], v[140:155]
	global_load_lds_dwordx4 v131, s[90:91]
	v_add_u32_e32 v131, 0x20000, v131
	ds_read_b128 v[236:239], v224 offset:32768
	ds_read_b128 v[240:243], v225 offset:32768
	s_waitcnt lgkmcnt(2)
	v_mfma_f32_32x32x16_bf16 v[140:155], v[216:219], v[164:167], v[140:155]
	s_add_i32 m0, s96, 0x8000
	v_mfma_f32_32x32x16_bf16 v[140:155], v[220:223], v[168:171], v[140:155]
	global_load_lds_dwordx4 v208, s[92:93]
	s_waitcnt lgkmcnt(0)
	v_mfma_f32_32x32x16_bf16 v[140:155], v[236:239], v[172:175], v[140:155]
	s_add_i32 m0, s96, 0xa000
	v_mfma_f32_32x32x16_bf16 v[140:155], v[240:243], v[232:235], v[140:155]
	global_load_lds_dwordx4 v208, s[94:95]
	v_add_u32_e32 v208, 0x20000, v208
	s_cmpk_gt_i32 s39, 0x7f
	s_cbranch_scc0 .Lattn_near1
	s_cmp_lg_u32 s67, 1
	s_cbranch_scc1 .Lattn_far1

; DI void phase_attn(int wid0, const Params& p, int L, unsigned char* lds, bool dry) {
;     ...
;                 float pmax = p0[0];
; #pragma unroll
;                 for (int r = 1; r < 16; ++r) pmax = fmaxf(pmax, p0[r]);
;                 { auto rr = __builtin_amdgcn_permlane32_swap(__float_as_uint(pmax), __float_as_uint(pmax), false, false); pmax = fmaxf(__uint_as_float(rr[0]), __uint_as_float(rr[1])); }
;                 float mn, alpha;
;                 if (__all(pmax - m_reg <= ATT_THR2)) { mn = m_reg; alpha = 1.f; }
;                 else { mn = fmaxf(m_reg, pmax); alpha = __builtin_amdgcn_exp2f(m_reg - mn); m_reg = mn; }
;                 float ps = 0.f;
; #pragma unroll
;                 for (int r = 0; r < 16; ++r) { p0[r] = __builtin_amdgcn_exp2f(p0[r] - mn); ps += p0[r]; }
;                 { auto rr = __builtin_amdgcn_permlane32_swap(__float_as_uint(ps), __float_as_uint(ps), false, false); ps = __uint_as_float(rr[0]) + __uint_as_float(rr[1]); }
;                 l_reg = l_reg * alpha + ps;
;                 __builtin_amdgcn_sched_barrier(0);
;                 bf16x8 pa0, pa1;
;     ...
;                 PK4(p0, 0, pa0); PK4(p0, 8, pa1);
;     ...
;                 __builtin_amdgcn_sched_barrier(0);
;                 if (__any(alpha < 1.f)) {
;                     if (hi == 0) al_l[r32] = alpha;
;                     asm volatile("s_waitcnt lgkmcnt(0)" ::: "memory");
;                     float ar[16];
; #pragma unroll
;                     for (int r = 0; r < 16; ++r) ar[r] = al_l[crow(r, hi)];
; #pragma unroll
;                     for (int d = 0; d < 8; ++d)
; #pragma unroll
;                         for (int r = 0; r < 16; ++r) o[d][r] *= ar[r];
;                 }
;                 __builtin_amdgcn_sched_barrier(0);
;                 LAS unsigned char* vbp = ldsl + 65536 + (t & 1) * 32768 + 16384 + v_rd_base(lane);
;                 __builtin_amdgcn_s_setprio(1);
;     ...
;                 {
;                     s16x4 a0, a1, a2, a3, b0_, b1_, b2_, b3_;
;                     PV_RD(0, a0, a1, a2, a3); SB();
;                     PV_RD(1, b0_, b1_, b2_, b3_); SB(); PV_MM(0, a0, a1, a2, a3); SB();
;                     PV_RD(2, a0, a1, a2, a3); SB(); PV_MM(1, b0_, b1_, b2_, b3_); SB();
;                     PV_RD(3, b0_, b1_, b2_, b3_); SB(); PV_MM(2, a0, a1, a2, a3); SB();
;                     PV_RD(4, a0, a1, a2, a3); SB(); PV_MM(3, b0_, b1_, b2_, b3_); SB();
.Lattn_region1:
	ds_read_b64_tr_b16 v[216:217], v212 offset:0
	ds_read_b64_tr_b16 v[218:219], v212 offset:4096
	ds_read_b64_tr_b16 v[220:221], v212 offset:8192
	ds_read_b64_tr_b16 v[222:223], v212 offset:12288
	ds_read_b64_tr_b16 v[236:237], v212 offset:512
	ds_read_b64_tr_b16 v[238:239], v212 offset:4608
	ds_read_b64_tr_b16 v[240:241], v212 offset:8704
	ds_read_b64_tr_b16 v[242:243], v212 offset:12800
	v_max3_f32 v226, v140, v141, v142
	v_max3_f32 v226, v226, v143, v144
	v_max3_f32 v226, v226, v145, v146
	v_max3_f32 v226, v226, v147, v148
	v_max3_f32 v226, v226, v149, v150
	v_max3_f32 v226, v226, v151, v152
	v_max3_f32 v226, v226, v153, v154
	v_max_f32_e32 v226, v226, v155
	v_mov_b32_e32 v227, v226
	s_nop 1
	v_permlane32_swap_b32_e32 v226, v227
	v_max_f32_e32 v226, v226, v227
	v_fma_f32 v226, v226, s82, v231
	v_sub_f32_e32 v227, v226, v213
	v_cmp_ge_f32_e32 vcc, s97, v227
	s_cmp_eq_u64 vcc, exec
	v_max_f32_e32 v226, v213, v226
	s_cselect_b64 vcc, -1, 0
	v_sub_f32_e32 v227, v213, v226
	v_cndmask_b32_e32 v213, v226, v213, vcc
	v_sub_f32_e32 v230, v231, v213
	s_waitcnt lgkmcnt(4)
	v_mfma_f32_32x32x16_bf16 v[114:129], v[156:159], v[216:219], v[114:129]
	v_mfma_f32_32x32x16_bf16 v[114:129], v[160:163], v[220:223], v[114:129]
	v_fma_f32 v140, v140, s82, v230
	v_exp_f32_e32 v140, v140
	v_fma_f32 v141, v141, s82, v230
	v_exp_f32_e32 v141, v141
	ds_read_b64_tr_b16 v[216:217], v212 offset:1024
	ds_read_b64_tr_b16 v[218:219], v212 offset:5120
	ds_read_b64_tr_b16 v[220:221], v212 offset:9216
	ds_read_b64_tr_b16 v[222:223], v212 offset:13312
	s_waitcnt lgkmcnt(4)
	v_mfma_f32_32x32x16_bf16 v[98:113], v[156:159], v[236:239], v[98:113]
	v_fma_f32 v142, v142, s82, v230
	v_exp_f32_e32 v142, v142
	v_add_f32_e32 v226, v140, v141
	v_fma_f32 v143, v143, s82, v230
	v_exp_f32_e32 v143, v143
	v_mfma_f32_32x32x16_bf16 v[98:113], v[160:163], v[240:243], v[98:113]
	v_add_f32_e32 v226, v226, v142
	v_fma_f32 v144, v144, s82, v230
	v_exp_f32_e32 v144, v144
	v_add_f32_e32 v226, v226, v143
	v_fma_f32 v145, v145, s82, v230
	ds_read_b64_tr_b16 v[236:237], v212 offset:1536
	ds_read_b64_tr_b16 v[238:239], v212 offset:5632
	ds_read_b64_tr_b16 v[240:241], v212 offset:9728
	ds_read_b64_tr_b16 v[242:243], v212 offset:13824
	s_waitcnt lgkmcnt(4)
	v_mfma_f32_32x32x16_bf16 v[82:97], v[156:159], v[216:219], v[82:97]
	v_exp_f32_e32 v145, v145
	v_add_f32_e32 v226, v226, v144
	v_fma_f32 v146, v146, s82, v230
	v_exp_f32_e32 v146, v146
	v_mfma_f32_32x32x16_bf16 v[82:97], v[160:163], v[220:223], v[82:97]
	v_add_f32_e32 v226, v226, v145
	v_fma_f32 v147, v147, s82, v230
	v_exp_f32_e32 v147, v147
	v_add_f32_e32 v226, v226, v146
	v_fma_f32 v148, v148, s82, v230
	ds_read_b64_tr_b16 v[216:217], v212 offset:2048
	ds_read_b64_tr_b16 v[218:219], v212 offset:6144
	ds_read_b64_tr_b16 v[220:221], v212 offset:10240
	ds_read_b64_tr_b16 v[222:223], v212 offset:14336
	s_waitcnt lgkmcnt(4)
	v_mfma_f32_32x32x16_bf16 v[66:81], v[156:159], v[236:239], v[66:81]
	v_exp_f32_e32 v148, v148
	v_add_f32_e32 v226, v226, v147
	v_fma_f32 v149, v149, s82, v230
	v_exp_f32_e32 v149, v149
	v_mfma_f32_32x32x16_bf16 v[66:81], v[160:163], v[240:243], v[66:81]
	v_add_f32_e32 v226, v226, v148
	v_fma_f32 v150, v150, s82, v230
	v_exp_f32_e32 v150, v150
	v_add_f32_e32 v226, v226, v149
	ds_read_b64_tr_b16 v[236:237], v212 offset:2560
	ds_read_b64_tr_b16 v[238:239], v212 offset:6656
	ds_read_b64_tr_b16 v[240:241], v212 offset:10752
	ds_read_b64_tr_b16 v[242:243], v212 offset:14848
	s_waitcnt lgkmcnt(4)
	v_mfma_f32_32x32x16_bf16 v[50:65], v[156:159], v[216:219], v[50:65]
	v_fma_f32 v151, v151, s82, v230
	v_exp_f32_e32 v151, v151
	v_add_f32_e32 v226, v226, v150
	v_fma_f32 v152, v152, s82, v230
	v_mfma_f32_32x32x16_bf16 v[50:65], v[160:163], v[220:223], v[50:65]
	v_exp_f32_e32 v152, v152
	v_add_f32_e32 v226, v226, v151
	v_fma_f32 v153, v153, s82, v230
	v_exp_f32_e32 v153, v153
	ds_read_b64_tr_b16 v[216:217], v212 offset:3072
	ds_read_b64_tr_b16 v[218:219], v212 offset:7168
	ds_read_b64_tr_b16 v[220:221], v212 offset:11264
	ds_read_b64_tr_b16 v[222:223], v212 offset:15360
	s_waitcnt lgkmcnt(4)
	v_mfma_f32_32x32x16_bf16 v[34:49], v[156:159], v[236:239], v[34:49]
	v_add_f32_e32 v226, v226, v152
	v_fma_f32 v154, v154, s82, v230
	v_exp_f32_e32 v154, v154
	v_add_f32_e32 v226, v226, v153
	v_mfma_f32_32x32x16_bf16 v[34:49], v[160:163], v[240:243], v[34:49]
	v_fma_f32 v155, v155, s82, v230
	v_exp_f32_e32 v155, v155
	v_add_f32_e32 v226, v226, v154
	v_exp_f32_e32 v227, v227
	ds_read_b64_tr_b16 v[236:237], v212 offset:3584
	ds_read_b64_tr_b16 v[238:239], v212 offset:7680
	ds_read_b64_tr_b16 v[240:241], v212 offset:11776
	ds_read_b64_tr_b16 v[242:243], v212 offset:15872
	s_waitcnt lgkmcnt(4)
	v_mfma_f32_32x32x16_bf16 v[18:33], v[156:159], v[216:219], v[18:33]
	v_add_f32_e32 v228, v226, v155
	v_cndmask_b32_e64 v227, v227, 1.0, vcc
	v_mov_b32_e32 v229, v228
	v_cvt_pk_bf16_f32 v132, v140, v141
	v_cvt_pk_bf16_f32 v133, v142, v143
	v_mfma_f32_32x32x16_bf16 v[18:33], v[160:163], v[220:223], v[18:33]
	v_cvt_pk_bf16_f32 v134, v144, v145
	v_cvt_pk_bf16_f32 v135, v146, v147
	v_cvt_pk_bf16_f32 v136, v148, v149
	v_cvt_pk_bf16_f32 v137, v150, v151
	v_cvt_pk_bf16_f32 v138, v152, v153
	s_waitcnt lgkmcnt(0)
	v_mfma_f32_32x32x16_bf16 v[2:17], v[156:159], v[236:239], v[2:17]
	v_cvt_pk_bf16_f32 v139, v154, v155
	v_permlane32_swap_b32_e32 v228, v229
	v_permlane32_swap_b32_e32 v132, v134
	v_permlane32_swap_b32_e32 v133, v135
	v_mfma_f32_32x32x16_bf16 v[2:17], v[160:163], v[240:243], v[2:17]
	v_permlane32_swap_b32_e32 v136, v138
	v_permlane32_swap_b32_e32 v137, v139
	v_add_f32_e32 v228, v228, v229
	v_fma_f32 v130, v130, v227, v228
	s_cbranch_vccnz .Lattn_norescale1
; DI int crow(int r, int hi) { return (r & 3) + 8 * (r >> 2) + 4 * hi; }
; DI void phase_attn(int wid0, const Params& p, int L, unsigned char* lds, bool dry) {
;     ...
;                 if (__any(alpha < 1.f)) {
;                     if (hi == 0) al_l[r32] = alpha;
;                     asm volatile("s_waitcnt lgkmcnt(0)" ::: "memory");
;                     float ar[16];
; #pragma unroll
;                     for (int r = 0; r < 16; ++r) ar[r] = al_l[crow(r, hi)];
; #pragma unroll
;                     for (int d = 0; d < 8; ++d)
; #pragma unroll
;                         for (int r = 0; r < 16; ++r) o[d][r] *= ar[r];
;                 }
	s_and_saveexec_b64 s[80:81], s[8:9]
	ds_write_b32 v196, v227 offset:128
	s_or_b64 exec, exec, s[80:81]
	s_waitcnt lgkmcnt(0)
	ds_read_b128 v[152:155], v214 offset:224
	ds_read_b128 v[148:151], v214 offset:192
	ds_read_b128 v[144:147], v214 offset:160
	ds_read_b128 v[140:143], v214 offset:128
	s_waitcnt lgkmcnt(0)
	v_pk_mul_f32 v[126:127], v[126:127], v[152:153]
	v_pk_mul_f32 v[122:123], v[122:123], v[148:149]
	v_pk_mul_f32 v[118:119], v[118:119], v[144:145]
	v_pk_mul_f32 v[128:129], v[128:129], v[154:155]
	v_pk_mul_f32 v[124:125], v[124:125], v[150:151]
	v_pk_mul_f32 v[120:121], v[120:121], v[146:147]
	v_pk_mul_f32 v[116:117], v[116:117], v[142:143]
	v_pk_mul_f32 v[114:115], v[114:115], v[140:141]
	v_pk_mul_f32 v[110:111], v[110:111], v[152:153]
	v_pk_mul_f32 v[106:107], v[106:107], v[148:149]
	v_pk_mul_f32 v[102:103], v[102:103], v[144:145]
	v_pk_mul_f32 v[112:113], v[112:113], v[154:155]
	v_pk_mul_f32 v[108:109], v[108:109], v[150:151]
	v_pk_mul_f32 v[104:105], v[104:105], v[146:147]
	v_pk_mul_f32 v[100:101], v[100:101], v[142:143]
	v_pk_mul_f32 v[98:99], v[98:99], v[140:141]
	v_pk_mul_f32 v[94:95], v[94:95], v[152:153]
	v_pk_mul_f32 v[90:91], v[90:91], v[148:149]
	v_pk_mul_f32 v[86:87], v[86:87], v[144:145]
	v_pk_mul_f32 v[96:97], v[96:97], v[154:155]
	v_pk_mul_f32 v[92:93], v[92:93], v[150:151]
	v_pk_mul_f32 v[88:89], v[88:89], v[146:147]
	v_pk_mul_f32 v[84:85], v[84:85], v[142:143]
	v_pk_mul_f32 v[82:83], v[82:83], v[140:141]
	v_pk_mul_f32 v[78:79], v[78:79], v[152:153]
	v_pk_mul_f32 v[74:75], v[74:75], v[148:149]
	v_pk_mul_f32 v[70:71], v[70:71], v[144:145]
	v_pk_mul_f32 v[80:81], v[80:81], v[154:155]
	v_pk_mul_f32 v[76:77], v[76:77], v[150:151]
	v_pk_mul_f32 v[72:73], v[72:73], v[146:147]
	v_pk_mul_f32 v[68:69], v[68:69], v[142:143]
	v_pk_mul_f32 v[66:67], v[66:67], v[140:141]
	v_pk_mul_f32 v[62:63], v[62:63], v[152:153]
	v_pk_mul_f32 v[58:59], v[58:59], v[148:149]
	v_pk_mul_f32 v[54:55], v[54:55], v[144:145]
	v_pk_mul_f32 v[64:65], v[64:65], v[154:155]
	v_pk_mul_f32 v[60:61], v[60:61], v[150:151]
	v_pk_mul_f32 v[56:57], v[56:57], v[146:147]
	v_pk_mul_f32 v[52:53], v[52:53], v[142:143]
	v_pk_mul_f32 v[50:51], v[50:51], v[140:141]
	v_pk_mul_f32 v[46:47], v[46:47], v[152:153]
	v_pk_mul_f32 v[42:43], v[42:43], v[148:149]
	v_pk_mul_f32 v[38:39], v[38:39], v[144:145]
	v_pk_mul_f32 v[48:49], v[48:49], v[154:155]
	v_pk_mul_f32 v[44:45], v[44:45], v[150:151]
	v_pk_mul_f32 v[40:41], v[40:41], v[146:147]
	v_pk_mul_f32 v[36:37], v[36:37], v[142:143]
	v_pk_mul_f32 v[34:35], v[34:35], v[140:141]
	v_pk_mul_f32 v[30:31], v[30:31], v[152:153]
	v_pk_mul_f32 v[26:27], v[26:27], v[148:149]
	v_pk_mul_f32 v[22:23], v[22:23], v[144:145]
	v_pk_mul_f32 v[32:33], v[32:33], v[154:155]
	v_pk_mul_f32 v[28:29], v[28:29], v[150:151]
	v_pk_mul_f32 v[24:25], v[24:25], v[146:147]
	v_pk_mul_f32 v[20:21], v[20:21], v[142:143]
	v_pk_mul_f32 v[18:19], v[18:19], v[140:141]
	v_pk_mul_f32 v[14:15], v[14:15], v[152:153]
	v_pk_mul_f32 v[10:11], v[10:11], v[148:149]
	v_pk_mul_f32 v[6:7], v[6:7], v[144:145]
	v_pk_mul_f32 v[16:17], v[16:17], v[154:155]
	v_pk_mul_f32 v[12:13], v[12:13], v[150:151]
	v_pk_mul_f32 v[8:9], v[8:9], v[146:147]
	v_pk_mul_f32 v[4:5], v[4:5], v[142:143]
	v_pk_mul_f32 v[2:3], v[2:3], v[140:141]

; #define LAS __attribute__((address_space(3)))
; DI void attn_stage(const bf16_t* kbase, const bf16_t* vbase, unsigned koff, unsigned voff, LAS unsigned char* ldsbuf, int wid) {
; #pragma unroll
;     for (int i = 0; i < 2; ++i) {
;         const char* src = (const char*)kbase + (size_t)(i * 128) * 2;
;         __builtin_amdgcn_global_load_lds((const unsigned*)(src + koff), (LAS unsigned*)(ldsbuf + (wid + 8 * i) * 1024), 16, 0, 0);
;     }
; #pragma unroll
;     for (int i = 0; i < 2; ++i) {
;         const char* src = (const char*)vbase + (size_t)(16 * i * 2048) * 2;
;         __builtin_amdgcn_global_load_lds((const unsigned*)(src + voff), (LAS unsigned*)(ldsbuf + 16384 + (wid + 8 * i) * 1024), 16, 0, 0);
;     }
; }
; DI void phase_attn(int wid0, const Params& p, int L, unsigned char* lds, bool dry) {
;     ...
;             asm volatile("s_waitcnt vmcnt(0) lgkmcnt(0)" ::: "memory"); __builtin_amdgcn_s_barrier(); asm volatile("" ::: "memory");
;             if (t + 1 < ntiles) attn_stage(kh_ + (size_t)(b * 4096 + 32 * t) * 2048, vh_ + (size_t)(b * 4096 + 32 * t) * 2048, koff, voff, ldsl + 65536 + ((t + 1) & 1) * 32768, wid);
;             const int kpos0 = (t == 0) ? 0 : 16 + 32 * (t - 1);
;             if (kpos0 <= wq0 + 31) {
;                 const unsigned char* Ks = lds + 65536 + (t & 1) * 32768 + psub * 8192;
;                 f32x16 p0, p0b;
; #pragma unroll
;                 for (int r = 0; r < 16; ++r) { p0[r] = 0.f; p0b[r] = 0.f; }
;                 int swz = (r32 & 6) << 4, kro = r32 * 256 + ((hi ^ (r32 & 1)) << 4); asm volatile("" : "+v"(swz), "+v"(kro));
; #pragma unroll
;                 for (int d0 = 0; d0 < 8; d0 += 2) {
;                     const bf16x8 b0 = *(const bf16x8*)(Ks + kro + ((d0 * 32) ^ swz));
;                     const bf16x8 qf = *(const bf16x8*)(qlds + d0 * 1024);
;                     const bf16x8 b1 = *(const bf16x8*)(Ks + kro + (((d0 + 1) * 32) ^ swz));
;                     const bf16x8 qg = *(const bf16x8*)(qlds + (d0 + 1) * 1024);
;                     p0 = MFMA32(b0, qf, p0);
;                     p0b = MFMA32(b1, qg, p0b);
;                     if (d0 == 2) __builtin_amdgcn_sched_barrier(0);
;                 }
; #pragma unroll
;                 for (int r = 0; r < 16; ++r) p0[r] += p0b[r];
;                 __builtin_amdgcn_sched_barrier(0);
.Lattn_top2:
	s_waitcnt vmcnt(0) lgkmcnt(0)
	s_barrier
	s_max_i32 s48, s7, 0
	s_cmp_gt_i32 s48, s38
	s_cbranch_scc1 .Lattn_skip2
	ds_read_b128 v[216:219], v188
	ds_read_b128 v[220:223], v177
	ds_read_b128 v[236:239], v209
	ds_read_b128 v[240:243], v210
	s_waitcnt lgkmcnt(2)
	v_mfma_f32_32x32x16_bf16 v[140:155], v[216:219], v[248:251], 0
	s_add_i32 m0, s4, 0x8000
	v_mfma_f32_32x32x16_bf16 v[140:155], v[220:223], v[252:255], v[140:155]
	global_load_lds_dwordx4 v131, s[88:89]
	ds_read_b128 v[216:219], v211
	ds_read_b128 v[220:223], v215
	s_waitcnt lgkmcnt(2)
	v_mfma_f32_32x32x16_bf16 v[140:155], v[236:239], v[200:203], v[140:155]
	s_add_i32 m0, s4, 0xa000
	v_mfma_f32_32x32x16_bf16 v[140:155], v[240:243], v[204:207], v[140:155]
	global_load_lds_dwordx4 v131, s[90:91]
	v_add_u32_e32 v131, 0x20000, v131
	ds_read_b128 v[236:239], v224
	ds_read_b128 v[240:243], v225
	s_waitcnt lgkmcnt(2)
	v_mfma_f32_32x32x16_bf16 v[140:155], v[216:219], v[164:167], v[140:155]
	s_add_i32 m0, s96, 0xc000
	v_mfma_f32_32x32x16_bf16 v[140:155], v[220:223], v[168:171], v[140:155]
	global_load_lds_dwordx4 v208, s[92:93]
	s_waitcnt lgkmcnt(0)
	v_mfma_f32_32x32x16_bf16 v[140:155], v[236:239], v[172:175], v[140:155]
	s_add_i32 m0, s96, 0xe000
	v_mfma_f32_32x32x16_bf16 v[140:155], v[240:243], v[232:235], v[140:155]
	global_load_lds_dwordx4 v208, s[94:95]
	v_add_u32_e32 v208, 0x20000, v208
	s_cmpk_gt_i32 s39, 0x7f
	s_cbranch_scc0 .Lattn_near2
	s_cmp_lg_u32 s67, 1
	s_cbranch_scc1 .Lattn_far2

; DI void phase_attn(int wid0, const Params& p, int L, unsigned char* lds, bool dry) {
;     ...
;                 float pmax = p0[0];
; #pragma unroll
;                 for (int r = 1; r < 16; ++r) pmax = fmaxf(pmax, p0[r]);
;                 { auto rr = __builtin_amdgcn_permlane32_swap(__float_as_uint(pmax), __float_as_uint(pmax), false, false); pmax = fmaxf(__uint_as_float(rr[0]), __uint_as_float(rr[1])); }
;                 float mn, alpha;
;                 if (__all(pmax - m_reg <= ATT_THR2)) { mn = m_reg; alpha = 1.f; }
;                 else { mn = fmaxf(m_reg, pmax); alpha = __builtin_amdgcn_exp2f(m_reg - mn); m_reg = mn; }
;                 float ps = 0.f;
; #pragma unroll
;                 for (int r = 0; r < 16; ++r) { p0[r] = __builtin_amdgcn_exp2f(p0[r] - mn); ps += p0[r]; }
;                 { auto rr = __builtin_amdgcn_permlane32_swap(__float_as_uint(ps), __float_as_uint(ps), false, false); ps = __uint_as_float(rr[0]) + __uint_as_float(rr[1]); }
;                 l_reg = l_reg * alpha + ps;
;                 __builtin_amdgcn_sched_barrier(0);
;                 bf16x8 pa0, pa1;
;     ...
;                 PK4(p0, 0, pa0); PK4(p0, 8, pa1);
;     ...
;                 __builtin_amdgcn_sched_barrier(0);
;                 if (__any(alpha < 1.f)) {
;                     if (hi == 0) al_l[r32] = alpha;
;                     asm volatile("s_waitcnt lgkmcnt(0)" ::: "memory");
;                     float ar[16];
; #pragma unroll
;                     for (int r = 0; r < 16; ++r) ar[r] = al_l[crow(r, hi)];
; #pragma unroll
;                     for (int d = 0; d < 8; ++d)
; #pragma unroll
;                         for (int r = 0; r < 16; ++r) o[d][r] *= ar[r];
;                 }
;                 __builtin_amdgcn_sched_barrier(0);
;                 LAS unsigned char* vbp = ldsl + 65536 + (t & 1) * 32768 + 16384 + v_rd_base(lane);
;                 __builtin_amdgcn_s_setprio(1);
;     ...
;                 {
;                     s16x4 a0, a1, a2, a3, b0_, b1_, b2_, b3_;
;                     PV_RD(0, a0, a1, a2, a3); SB();
;                     PV_RD(1, b0_, b1_, b2_, b3_); SB(); PV_MM(0, a0, a1, a2, a3); SB();
;                     PV_RD(2, a0, a1, a2, a3); SB(); PV_MM(1, b0_, b1_, b2_, b3_); SB();
;                     PV_RD(3, b0_, b1_, b2_, b3_); SB(); PV_MM(2, a0, a1, a2, a3); SB();
;                     PV_RD(4, a0, a1, a2, a3); SB(); PV_MM(3, b0_, b1_, b2_, b3_); SB();
.Lattn_region2:
	ds_read_b64_tr_b16 v[216:217], v212 offset:16384
	ds_read_b64_tr_b16 v[218:219], v212 offset:20480
	ds_read_b64_tr_b16 v[220:221], v212 offset:24576
	ds_read_b64_tr_b16 v[222:223], v212 offset:28672
	ds_read_b64_tr_b16 v[236:237], v212 offset:16896
	ds_read_b64_tr_b16 v[238:239], v212 offset:20992
	ds_read_b64_tr_b16 v[240:241], v212 offset:25088
	ds_read_b64_tr_b16 v[242:243], v212 offset:29184
	v_max3_f32 v226, v140, v141, v142
	v_max3_f32 v226, v226, v143, v144
	v_max3_f32 v226, v226, v145, v146
	v_max3_f32 v226, v226, v147, v148
	v_max3_f32 v226, v226, v149, v150
	v_max3_f32 v226, v226, v151, v152
	v_max3_f32 v226, v226, v153, v154
	v_max_f32_e32 v226, v226, v155
	v_mov_b32_e32 v227, v226
	s_nop 1
	v_permlane32_swap_b32_e32 v226, v227
	v_max_f32_e32 v226, v226, v227
	v_fma_f32 v226, v226, s82, v231
	v_sub_f32_e32 v227, v226, v213
	v_cmp_ge_f32_e32 vcc, s97, v227
	s_cmp_eq_u64 vcc, exec
	v_max_f32_e32 v226, v213, v226
	s_cselect_b64 vcc, -1, 0
	v_sub_f32_e32 v227, v213, v226
	v_cndmask_b32_e32 v213, v226, v213, vcc
	v_sub_f32_e32 v230, v231, v213
	s_waitcnt lgkmcnt(4)
	v_mfma_f32_32x32x16_bf16 v[114:129], v[132:135], v[216:219], v[114:129]
	v_mfma_f32_32x32x16_bf16 v[114:129], v[136:139], v[220:223], v[114:129]
	v_fma_f32 v140, v140, s82, v230
	v_exp_f32_e32 v140, v140
	v_fma_f32 v141, v141, s82, v230
	v_exp_f32_e32 v141, v141
	ds_read_b64_tr_b16 v[216:217], v212 offset:17408
	ds_read_b64_tr_b16 v[218:219], v212 offset:21504
	ds_read_b64_tr_b16 v[220:221], v212 offset:25600
	ds_read_b64_tr_b16 v[222:223], v212 offset:29696
	s_waitcnt lgkmcnt(4)
	v_mfma_f32_32x32x16_bf16 v[98:113], v[132:135], v[236:239], v[98:113]
	v_fma_f32 v142, v142, s82, v230
	v_exp_f32_e32 v142, v142
	v_add_f32_e32 v226, v140, v141
	v_fma_f32 v143, v143, s82, v230
	v_exp_f32_e32 v143, v143
	v_mfma_f32_32x32x16_bf16 v[98:113], v[136:139], v[240:243], v[98:113]
	v_add_f32_e32 v226, v226, v142
	v_fma_f32 v144, v144, s82, v230
	v_exp_f32_e32 v144, v144
	v_add_f32_e32 v226, v226, v143
	v_fma_f32 v145, v145, s82, v230
	ds_read_b64_tr_b16 v[236:237], v212 offset:17920
	ds_read_b64_tr_b16 v[238:239], v212 offset:22016
	ds_read_b64_tr_b16 v[240:241], v212 offset:26112
	ds_read_b64_tr_b16 v[242:243], v212 offset:30208
	s_waitcnt lgkmcnt(4)
	v_mfma_f32_32x32x16_bf16 v[82:97], v[132:135], v[216:219], v[82:97]
	v_exp_f32_e32 v145, v145
	v_add_f32_e32 v226, v226, v144
	v_fma_f32 v146, v146, s82, v230
	v_exp_f32_e32 v146, v146
	v_mfma_f32_32x32x16_bf16 v[82:97], v[136:139], v[220:223], v[82:97]
	v_add_f32_e32 v226, v226, v145
	v_fma_f32 v147, v147, s82, v230
	v_exp_f32_e32 v147, v147
	v_add_f32_e32 v226, v226, v146
	v_fma_f32 v148, v148, s82, v230
	ds_read_b64_tr_b16 v[216:217], v212 offset:18432
	ds_read_b64_tr_b16 v[218:219], v212 offset:22528
	ds_read_b64_tr_b16 v[220:221], v212 offset:26624
	ds_read_b64_tr_b16 v[222:223], v212 offset:30720
	s_waitcnt lgkmcnt(4)
	v_mfma_f32_32x32x16_bf16 v[66:81], v[132:135], v[236:239], v[66:81]
	v_exp_f32_e32 v148, v148
	v_add_f32_e32 v226, v226, v147
	v_fma_f32 v149, v149, s82, v230
	v_exp_f32_e32 v149, v149
	v_mfma_f32_32x32x16_bf16 v[66:81], v[136:139], v[240:243], v[66:81]
	v_add_f32_e32 v226, v226, v148
	v_fma_f32 v150, v150, s82, v230
	v_exp_f32_e32 v150, v150
	v_add_f32_e32 v226, v226, v149
	ds_read_b64_tr_b16 v[236:237], v212 offset:18944
	ds_read_b64_tr_b16 v[238:239], v212 offset:23040
	ds_read_b64_tr_b16 v[240:241], v212 offset:27136
	ds_read_b64_tr_b16 v[242:243], v212 offset:31232
	s_waitcnt lgkmcnt(4)
	v_mfma_f32_32x32x16_bf16 v[50:65], v[132:135], v[216:219], v[50:65]
	v_fma_f32 v151, v151, s82, v230
	v_exp_f32_e32 v151, v151
	v_add_f32_e32 v226, v226, v150
	v_fma_f32 v152, v152, s82, v230
	v_mfma_f32_32x32x16_bf16 v[50:65], v[136:139], v[220:223], v[50:65]
	v_exp_f32_e32 v152, v152
	v_add_f32_e32 v226, v226, v151
	v_fma_f32 v153, v153, s82, v230
	v_exp_f32_e32 v153, v153
	ds_read_b64_tr_b16 v[216:217], v212 offset:19456
	ds_read_b64_tr_b16 v[218:219], v212 offset:23552
	ds_read_b64_tr_b16 v[220:221], v212 offset:27648
	ds_read_b64_tr_b16 v[222:223], v212 offset:31744
	s_waitcnt lgkmcnt(4)
	v_mfma_f32_32x32x16_bf16 v[34:49], v[132:135], v[236:239], v[34:49]
	v_add_f32_e32 v226, v226, v152
	v_fma_f32 v154, v154, s82, v230
	v_exp_f32_e32 v154, v154
	v_add_f32_e32 v226, v226, v153
	v_mfma_f32_32x32x16_bf16 v[34:49], v[136:139], v[240:243], v[34:49]
	v_fma_f32 v155, v155, s82, v230
	v_exp_f32_e32 v155, v155
	v_add_f32_e32 v226, v226, v154
	v_exp_f32_e32 v227, v227
	ds_read_b64_tr_b16 v[236:237], v212 offset:19968
	ds_read_b64_tr_b16 v[238:239], v212 offset:24064
	ds_read_b64_tr_b16 v[240:241], v212 offset:28160
	ds_read_b64_tr_b16 v[242:243], v212 offset:32256
	s_waitcnt lgkmcnt(4)
	v_mfma_f32_32x32x16_bf16 v[18:33], v[132:135], v[216:219], v[18:33]
	v_add_f32_e32 v228, v226, v155
	v_cndmask_b32_e64 v227, v227, 1.0, vcc
	v_mov_b32_e32 v229, v228
	v_cvt_pk_bf16_f32 v156, v140, v141
	v_cvt_pk_bf16_f32 v157, v142, v143
	v_mfma_f32_32x32x16_bf16 v[18:33], v[136:139], v[220:223], v[18:33]
	v_cvt_pk_bf16_f32 v158, v144, v145
	v_cvt_pk_bf16_f32 v159, v146, v147
	v_cvt_pk_bf16_f32 v160, v148, v149
	v_cvt_pk_bf16_f32 v161, v150, v151
	v_cvt_pk_bf16_f32 v162, v152, v153
	s_waitcnt lgkmcnt(0)
	v_mfma_f32_32x32x16_bf16 v[2:17], v[132:135], v[236:239], v[2:17]
	v_cvt_pk_bf16_f32 v163, v154, v155
	v_permlane32_swap_b32_e32 v228, v229
	v_permlane32_swap_b32_e32 v156, v158
	v_permlane32_swap_b32_e32 v157, v159
	v_mfma_f32_32x32x16_bf16 v[2:17], v[136:139], v[240:243], v[2:17]
	v_permlane32_swap_b32_e32 v160, v162
	v_permlane32_swap_b32_e32 v161, v163
	v_add_f32_e32 v228, v228, v229
	v_fma_f32 v130, v130, v227, v228
	s_cbranch_vccnz .Lattn_norescale2
; DI int crow(int r, int hi) { return (r & 3) + 8 * (r >> 2) + 4 * hi; }
; DI void phase_attn(int wid0, const Params& p, int L, unsigned char* lds, bool dry) {
;     ...
;                 if (__any(alpha < 1.f)) {
;                     if (hi == 0) al_l[r32] = alpha;
;                     asm volatile("s_waitcnt lgkmcnt(0)" ::: "memory");
;                     float ar[16];
; #pragma unroll
;                     for (int r = 0; r < 16; ++r) ar[r] = al_l[crow(r, hi)];
; #pragma unroll
;                     for (int d = 0; d < 8; ++d)
; #pragma unroll
;                         for (int r = 0; r < 16; ++r) o[d][r] *= ar[r];
;                 }
	s_and_saveexec_b64 s[80:81], s[8:9]
	ds_write_b32 v196, v227 offset:128
	s_or_b64 exec, exec, s[80:81]
	s_waitcnt lgkmcnt(0)
	ds_read_b128 v[152:155], v214 offset:224
	ds_read_b128 v[148:151], v214 offset:192
	ds_read_b128 v[144:147], v214 offset:160
	ds_read_b128 v[140:143], v214 offset:128
	s_waitcnt lgkmcnt(0)
	v_pk_mul_f32 v[126:127], v[126:127], v[152:153]
	v_pk_mul_f32 v[122:123], v[122:123], v[148:149]
	v_pk_mul_f32 v[118:119], v[118:119], v[144:145]
	v_pk_mul_f32 v[128:129], v[128:129], v[154:155]
	v_pk_mul_f32 v[124:125], v[124:125], v[150:151]
	v_pk_mul_f32 v[120:121], v[120:121], v[146:147]
	v_pk_mul_f32 v[116:117], v[116:117], v[142:143]
	v_pk_mul_f32 v[114:115], v[114:115], v[140:141]
	v_pk_mul_f32 v[110:111], v[110:111], v[152:153]
	v_pk_mul_f32 v[106:107], v[106:107], v[148:149]
	v_pk_mul_f32 v[102:103], v[102:103], v[144:145]
	v_pk_mul_f32 v[112:113], v[112:113], v[154:155]
	v_pk_mul_f32 v[108:109], v[108:109], v[150:151]
	v_pk_mul_f32 v[104:105], v[104:105], v[146:147]
	v_pk_mul_f32 v[100:101], v[100:101], v[142:143]
	v_pk_mul_f32 v[98:99], v[98:99], v[140:141]
	v_pk_mul_f32 v[94:95], v[94:95], v[152:153]
	v_pk_mul_f32 v[90:91], v[90:91], v[148:149]
	v_pk_mul_f32 v[86:87], v[86:87], v[144:145]
	v_pk_mul_f32 v[96:97], v[96:97], v[154:155]
	v_pk_mul_f32 v[92:93], v[92:93], v[150:151]
	v_pk_mul_f32 v[88:89], v[88:89], v[146:147]
	v_pk_mul_f32 v[84:85], v[84:85], v[142:143]
	v_pk_mul_f32 v[82:83], v[82:83], v[140:141]
	v_pk_mul_f32 v[78:79], v[78:79], v[152:153]
	v_pk_mul_f32 v[74:75], v[74:75], v[148:149]
	v_pk_mul_f32 v[70:71], v[70:71], v[144:145]
	v_pk_mul_f32 v[80:81], v[80:81], v[154:155]
	v_pk_mul_f32 v[76:77], v[76:77], v[150:151]
	v_pk_mul_f32 v[72:73], v[72:73], v[146:147]
	v_pk_mul_f32 v[68:69], v[68:69], v[142:143]
	v_pk_mul_f32 v[66:67], v[66:67], v[140:141]
	v_pk_mul_f32 v[62:63], v[62:63], v[152:153]
	v_pk_mul_f32 v[58:59], v[58:59], v[148:149]
	v_pk_mul_f32 v[54:55], v[54:55], v[144:145]
	v_pk_mul_f32 v[64:65], v[64:65], v[154:155]
	v_pk_mul_f32 v[60:61], v[60:61], v[150:151]
	v_pk_mul_f32 v[56:57], v[56:57], v[146:147]
	v_pk_mul_f32 v[52:53], v[52:53], v[142:143]
	v_pk_mul_f32 v[50:51], v[50:51], v[140:141]
	v_pk_mul_f32 v[46:47], v[46:47], v[152:153]
	v_pk_mul_f32 v[42:43], v[42:43], v[148:149]
	v_pk_mul_f32 v[38:39], v[38:39], v[144:145]
	v_pk_mul_f32 v[48:49], v[48:49], v[154:155]
	v_pk_mul_f32 v[44:45], v[44:45], v[150:151]
	v_pk_mul_f32 v[40:41], v[40:41], v[146:147]
	v_pk_mul_f32 v[36:37], v[36:37], v[142:143]
	v_pk_mul_f32 v[34:35], v[34:35], v[140:141]
	v_pk_mul_f32 v[30:31], v[30:31], v[152:153]
	v_pk_mul_f32 v[26:27], v[26:27], v[148:149]
	v_pk_mul_f32 v[22:23], v[22:23], v[144:145]
	v_pk_mul_f32 v[32:33], v[32:33], v[154:155]
	v_pk_mul_f32 v[28:29], v[28:29], v[150:151]
	v_pk_mul_f32 v[24:25], v[24:25], v[146:147]
	v_pk_mul_f32 v[20:21], v[20:21], v[142:143]
	v_pk_mul_f32 v[18:19], v[18:19], v[140:141]
	v_pk_mul_f32 v[14:15], v[14:15], v[152:153]
	v_pk_mul_f32 v[10:11], v[10:11], v[148:149]
	v_pk_mul_f32 v[6:7], v[6:7], v[144:145]
	v_pk_mul_f32 v[16:17], v[16:17], v[154:155]
	v_pk_mul_f32 v[12:13], v[12:13], v[150:151]
	v_pk_mul_f32 v[8:9], v[8:9], v[146:147]
	v_pk_mul_f32 v[4:5], v[4:5], v[142:143]
	v_pk_mul_f32 v[2:3], v[2:3], v[140:141]

; #define LAS __attribute__((address_space(3)))
; DI void attn_stage(const bf16_t* kbase, const bf16_t* vbase, unsigned koff, unsigned voff, LAS unsigned char* ldsbuf, int wid) {
; #pragma unroll
;     for (int i = 0; i < 2; ++i) {
;         const char* src = (const char*)kbase + (size_t)(i * 128) * 2;
;         __builtin_amdgcn_global_load_lds((const unsigned*)(src + koff), (LAS unsigned*)(ldsbuf + (wid + 8 * i) * 1024), 16, 0, 0);
;     }
; #pragma unroll
;     for (int i = 0; i < 2; ++i) {
;         const char* src = (const char*)vbase + (size_t)(16 * i * 2048) * 2;
;         __builtin_amdgcn_global_load_lds((const unsigned*)(src + voff), (LAS unsigned*)(ldsbuf + 16384 + (wid + 8 * i) * 1024), 16, 0, 0);
;     }
; }
; DI void phase_attn(int wid0, const Params& p, int L, unsigned char* lds, bool dry) {
;     ...
;             asm volatile("s_waitcnt vmcnt(0) lgkmcnt(0)" ::: "memory"); __builtin_amdgcn_s_barrier(); asm volatile("" ::: "memory");
;             if (t + 1 < ntiles) attn_stage(kh_ + (size_t)(b * 4096 + 32 * t) * 2048, vh_ + (size_t)(b * 4096 + 32 * t) * 2048, koff, voff, ldsl + 65536 + ((t + 1) & 1) * 32768, wid);
;             const int kpos0 = (t == 0) ? 0 : 16 + 32 * (t - 1);
;             if (kpos0 <= wq0 + 31) {
;                 const unsigned char* Ks = lds + 65536 + (t & 1) * 32768 + psub * 8192;
;                 f32x16 p0, p0b;
; #pragma unroll
;                 for (int r = 0; r < 16; ++r) { p0[r] = 0.f; p0b[r] = 0.f; }
;                 int swz = (r32 & 6) << 4, kro = r32 * 256 + ((hi ^ (r32 & 1)) << 4); asm volatile("" : "+v"(swz), "+v"(kro));
; #pragma unroll
;                 for (int d0 = 0; d0 < 8; d0 += 2) {
;                     const bf16x8 b0 = *(const bf16x8*)(Ks + kro + ((d0 * 32) ^ swz));
;                     const bf16x8 qf = *(const bf16x8*)(qlds + d0 * 1024);
;                     const bf16x8 b1 = *(const bf16x8*)(Ks + kro + (((d0 + 1) * 32) ^ swz));
;                     const bf16x8 qg = *(const bf16x8*)(qlds + (d0 + 1) * 1024);
;                     p0 = MFMA32(b0, qf, p0);
;                     p0b = MFMA32(b1, qg, p0b);
;                     if (d0 == 2) __builtin_amdgcn_sched_barrier(0);
;                 }
; #pragma unroll
;                 for (int r = 0; r < 16; ++r) p0[r] += p0b[r];
;                 __builtin_amdgcn_sched_barrier(0);
.Lattn_top3:
	s_waitcnt vmcnt(0) lgkmcnt(0)
	s_barrier
	s_max_i32 s48, s7, 0
	s_cmp_gt_i32 s48, s38
	s_cbranch_scc1 .Lattn_skip3
	ds_read_b128 v[216:219], v188 offset:32768
	ds_read_b128 v[220:223], v177 offset:32768
	ds_read_b128 v[236:239], v209 offset:32768
	ds_read_b128 v[240:243], v210 offset:32768
	s_waitcnt lgkmcnt(2)
	v_mfma_f32_32x32x16_bf16 v[140:155], v[216:219], v[248:251], 0
	s_add_i32 m0, s4, 0x0
	v_mfma_f32_32x32x16_bf16 v[140:155], v[220:223], v[252:255], v[140:155]
	global_load_lds_dwordx4 v131, s[88:89]
	ds_read_b128 v[216:219], v211 offset:32768
	ds_read_b128 v[220:223], v215 offset:32768
	s_waitcnt lgkmcnt(2)
	v_mfma_f32_32x32x16_bf16 v[140:155], v[236:239], v[200:203], v[140:155]
	s_add_i32 m0, s4, 0x2000
	v_mfma_f32_32x32x16_bf16 v[140:155], v[240:243], v[204:207], v[140:155]
	global_load_lds_dwordx4 v131, s[90:91]
	v_add_u32_e32 v131, 0x20000, v131
	ds_read_b128 v[236:239], v224 offset:32768
	ds_read_b128 v[240:243], v225 offset:32768
	s_waitcnt lgkmcnt(2)
	v_mfma_f32_32x32x16_bf16 v[140:155], v[216:219], v[164:167], v[140:155]
	s_add_i32 m0, s96, 0x0
	v_mfma_f32_32x32x16_bf16 v[140:155], v[220:223], v[168:171], v[140:155]
	global_load_lds_dwordx4 v208, s[92:93]
	s_waitcnt lgkmcnt(0)
	v_mfma_f32_32x32x16_bf16 v[140:155], v[236:239], v[172:175], v[140:155]
	s_add_i32 m0, s96, 0x2000
	v_mfma_f32_32x32x16_bf16 v[140:155], v[240:243], v[232:235], v[140:155]
	global_load_lds_dwordx4 v208, s[94:95]
	v_add_u32_e32 v208, 0x20000, v208
	s_cmpk_gt_i32 s39, 0x7f
	s_cbranch_scc0 .Lattn_near3
	s_cmp_lg_u32 s67, 1
	s_cbranch_scc1 .Lattn_far3

; DI void phase_attn(int wid0, const Params& p, int L, unsigned char* lds, bool dry) {
;     ...
;                 float pmax = p0[0];
; #pragma unroll
;                 for (int r = 1; r < 16; ++r) pmax = fmaxf(pmax, p0[r]);
;                 { auto rr = __builtin_amdgcn_permlane32_swap(__float_as_uint(pmax), __float_as_uint(pmax), false, false); pmax = fmaxf(__uint_as_float(rr[0]), __uint_as_float(rr[1])); }
;                 float mn, alpha;
;                 if (__all(pmax - m_reg <= ATT_THR2)) { mn = m_reg; alpha = 1.f; }
;                 else { mn = fmaxf(m_reg, pmax); alpha = __builtin_amdgcn_exp2f(m_reg - mn); m_reg = mn; }
;                 float ps = 0.f;
; #pragma unroll
;                 for (int r = 0; r < 16; ++r) { p0[r] = __builtin_amdgcn_exp2f(p0[r] - mn); ps += p0[r]; }
;                 { auto rr = __builtin_amdgcn_permlane32_swap(__float_as_uint(ps), __float_as_uint(ps), false, false); ps = __uint_as_float(rr[0]) + __uint_as_float(rr[1]); }
;                 l_reg = l_reg * alpha + ps;
;                 __builtin_amdgcn_sched_barrier(0);
;                 bf16x8 pa0, pa1;
;     ...
;                 PK4(p0, 0, pa0); PK4(p0, 8, pa1);
;     ...
;                 __builtin_amdgcn_sched_barrier(0);
;                 if (__any(alpha < 1.f)) {
;                     if (hi == 0) al_l[r32] = alpha;
;                     asm volatile("s_waitcnt lgkmcnt(0)" ::: "memory");
;                     float ar[16];
; #pragma unroll
;                     for (int r = 0; r < 16; ++r) ar[r] = al_l[crow(r, hi)];
; #pragma unroll
;                     for (int d = 0; d < 8; ++d)
; #pragma unroll
;                         for (int r = 0; r < 16; ++r) o[d][r] *= ar[r];
;                 }
;                 __builtin_amdgcn_sched_barrier(0);
;                 LAS unsigned char* vbp = ldsl + 65536 + (t & 1) * 32768 + 16384 + v_rd_base(lane);
;                 __builtin_amdgcn_s_setprio(1);
;     ...
;                 {
;                     s16x4 a0, a1, a2, a3, b0_, b1_, b2_, b3_;
;                     PV_RD(0, a0, a1, a2, a3); SB();
;                     PV_RD(1, b0_, b1_, b2_, b3_); SB(); PV_MM(0, a0, a1, a2, a3); SB();
;                     PV_RD(2, a0, a1, a2, a3); SB(); PV_MM(1, b0_, b1_, b2_, b3_); SB();
;                     PV_RD(3, b0_, b1_, b2_, b3_); SB(); PV_MM(2, a0, a1, a2, a3); SB();
;                     PV_RD(4, a0, a1, a2, a3); SB(); PV_MM(3, b0_, b1_, b2_, b3_); SB();
.Lattn_region3:
	ds_read_b64_tr_b16 v[216:217], v212 offset:32768
	ds_read_b64_tr_b16 v[218:219], v212 offset:36864
	ds_read_b64_tr_b16 v[220:221], v212 offset:40960
	ds_read_b64_tr_b16 v[222:223], v212 offset:45056
	ds_read_b64_tr_b16 v[236:237], v212 offset:33280
	ds_read_b64_tr_b16 v[238:239], v212 offset:37376
	ds_read_b64_tr_b16 v[240:241], v212 offset:41472
	ds_read_b64_tr_b16 v[242:243], v212 offset:45568
	v_max3_f32 v226, v140, v141, v142
	v_max3_f32 v226, v226, v143, v144
	v_max3_f32 v226, v226, v145, v146
	v_max3_f32 v226, v226, v147, v148
	v_max3_f32 v226, v226, v149, v150
	v_max3_f32 v226, v226, v151, v152
	v_max3_f32 v226, v226, v153, v154
	v_max_f32_e32 v226, v226, v155
	v_mov_b32_e32 v227, v226
	s_nop 1
	v_permlane32_swap_b32_e32 v226, v227
	v_max_f32_e32 v226, v226, v227
	v_fma_f32 v226, v226, s82, v231
	v_sub_f32_e32 v227, v226, v213
	v_cmp_ge_f32_e32 vcc, s97, v227
	s_cmp_eq_u64 vcc, exec
	v_max_f32_e32 v226, v213, v226
	s_cselect_b64 vcc, -1, 0
	v_sub_f32_e32 v227, v213, v226
	v_cndmask_b32_e32 v213, v226, v213, vcc
	v_sub_f32_e32 v230, v231, v213
	s_waitcnt lgkmcnt(4)
	v_mfma_f32_32x32x16_bf16 v[114:129], v[156:159], v[216:219], v[114:129]
	v_mfma_f32_32x32x16_bf16 v[114:129], v[160:163], v[220:223], v[114:129]
	v_fma_f32 v140, v140, s82, v230
	v_exp_f32_e32 v140, v140
	v_fma_f32 v141, v141, s82, v230
	v_exp_f32_e32 v141, v141
	ds_read_b64_tr_b16 v[216:217], v212 offset:33792
	ds_read_b64_tr_b16 v[218:219], v212 offset:37888
	ds_read_b64_tr_b16 v[220:221], v212 offset:41984
	ds_read_b64_tr_b16 v[222:223], v212 offset:46080
	s_waitcnt lgkmcnt(4)
	v_mfma_f32_32x32x16_bf16 v[98:113], v[156:159], v[236:239], v[98:113]
	v_fma_f32 v142, v142, s82, v230
	v_exp_f32_e32 v142, v142
	v_add_f32_e32 v226, v140, v141
	v_fma_f32 v143, v143, s82, v230
	v_exp_f32_e32 v143, v143
	v_mfma_f32_32x32x16_bf16 v[98:113], v[160:163], v[240:243], v[98:113]
	v_add_f32_e32 v226, v226, v142
	v_fma_f32 v144, v144, s82, v230
	v_exp_f32_e32 v144, v144
	v_add_f32_e32 v226, v226, v143
	v_fma_f32 v145, v145, s82, v230
	ds_read_b64_tr_b16 v[236:237], v212 offset:34304
	ds_read_b64_tr_b16 v[238:239], v212 offset:38400
	ds_read_b64_tr_b16 v[240:241], v212 offset:42496
	ds_read_b64_tr_b16 v[242:243], v212 offset:46592
	s_waitcnt lgkmcnt(4)
	v_mfma_f32_32x32x16_bf16 v[82:97], v[156:159], v[216:219], v[82:97]
	v_exp_f32_e32 v145, v145
	v_add_f32_e32 v226, v226, v144
	v_fma_f32 v146, v146, s82, v230
	v_exp_f32_e32 v146, v146
	v_mfma_f32_32x32x16_bf16 v[82:97], v[160:163], v[220:223], v[82:97]
	v_add_f32_e32 v226, v226, v145
	v_fma_f32 v147, v147, s82, v230
	v_exp_f32_e32 v147, v147
	v_add_f32_e32 v226, v226, v146
	v_fma_f32 v148, v148, s82, v230
	ds_read_b64_tr_b16 v[216:217], v212 offset:34816
	ds_read_b64_tr_b16 v[218:219], v212 offset:38912
	ds_read_b64_tr_b16 v[220:221], v212 offset:43008
	ds_read_b64_tr_b16 v[222:223], v212 offset:47104
	s_waitcnt lgkmcnt(4)
	v_mfma_f32_32x32x16_bf16 v[66:81], v[156:159], v[236:239], v[66:81]
	v_exp_f32_e32 v148, v148
	v_add_f32_e32 v226, v226, v147
	v_fma_f32 v149, v149, s82, v230
	v_exp_f32_e32 v149, v149
	v_mfma_f32_32x32x16_bf16 v[66:81], v[160:163], v[240:243], v[66:81]
	v_add_f32_e32 v226, v226, v148
	v_fma_f32 v150, v150, s82, v230
	v_exp_f32_e32 v150, v150
	v_add_f32_e32 v226, v226, v149
	ds_read_b64_tr_b16 v[236:237], v212 offset:35328
	ds_read_b64_tr_b16 v[238:239], v212 offset:39424
	ds_read_b64_tr_b16 v[240:241], v212 offset:43520
	ds_read_b64_tr_b16 v[242:243], v212 offset:47616
	s_waitcnt lgkmcnt(4)
	v_mfma_f32_32x32x16_bf16 v[50:65], v[156:159], v[216:219], v[50:65]
	v_fma_f32 v151, v151, s82, v230
	v_exp_f32_e32 v151, v151
	v_add_f32_e32 v226, v226, v150
	v_fma_f32 v152, v152, s82, v230
	v_mfma_f32_32x32x16_bf16 v[50:65], v[160:163], v[220:223], v[50:65]
	v_exp_f32_e32 v152, v152
	v_add_f32_e32 v226, v226, v151
	v_fma_f32 v153, v153, s82, v230
	v_exp_f32_e32 v153, v153
	ds_read_b64_tr_b16 v[216:217], v212 offset:35840
	ds_read_b64_tr_b16 v[218:219], v212 offset:39936
	ds_read_b64_tr_b16 v[220:221], v212 offset:44032
	ds_read_b64_tr_b16 v[222:223], v212 offset:48128
	s_waitcnt lgkmcnt(4)
	v_mfma_f32_32x32x16_bf16 v[34:49], v[156:159], v[236:239], v[34:49]
	v_add_f32_e32 v226, v226, v152
	v_fma_f32 v154, v154, s82, v230
	v_exp_f32_e32 v154, v154
	v_add_f32_e32 v226, v226, v153
	v_mfma_f32_32x32x16_bf16 v[34:49], v[160:163], v[240:243], v[34:49]
	v_fma_f32 v155, v155, s82, v230
	v_exp_f32_e32 v155, v155
	v_add_f32_e32 v226, v226, v154
	v_exp_f32_e32 v227, v227
	ds_read_b64_tr_b16 v[236:237], v212 offset:36352
	ds_read_b64_tr_b16 v[238:239], v212 offset:40448
	ds_read_b64_tr_b16 v[240:241], v212 offset:44544
	ds_read_b64_tr_b16 v[242:243], v212 offset:48640
	s_waitcnt lgkmcnt(4)
	v_mfma_f32_32x32x16_bf16 v[18:33], v[156:159], v[216:219], v[18:33]
	v_add_f32_e32 v228, v226, v155
	v_cndmask_b32_e64 v227, v227, 1.0, vcc
	v_mov_b32_e32 v229, v228
	v_cvt_pk_bf16_f32 v132, v140, v141
	v_cvt_pk_bf16_f32 v133, v142, v143
	v_mfma_f32_32x32x16_bf16 v[18:33], v[160:163], v[220:223], v[18:33]
	v_cvt_pk_bf16_f32 v134, v144, v145
	v_cvt_pk_bf16_f32 v135, v146, v147
	v_cvt_pk_bf16_f32 v136, v148, v149
	v_cvt_pk_bf16_f32 v137, v150, v151
	v_cvt_pk_bf16_f32 v138, v152, v153
	s_waitcnt lgkmcnt(0)
	v_mfma_f32_32x32x16_bf16 v[2:17], v[156:159], v[236:239], v[2:17]
	v_cvt_pk_bf16_f32 v139, v154, v155
	v_permlane32_swap_b32_e32 v228, v229
	v_permlane32_swap_b32_e32 v132, v134
	v_permlane32_swap_b32_e32 v133, v135
	v_mfma_f32_32x32x16_bf16 v[2:17], v[160:163], v[240:243], v[2:17]
	v_permlane32_swap_b32_e32 v136, v138
	v_permlane32_swap_b32_e32 v137, v139
	v_add_f32_e32 v228, v228, v229
	v_fma_f32 v130, v130, v227, v228
	s_cbranch_vccnz .Lattn_norescale3
; DI int crow(int r, int hi) { return (r & 3) + 8 * (r >> 2) + 4 * hi; }
; DI void phase_attn(int wid0, const Params& p, int L, unsigned char* lds, bool dry) {
;     ...
;                 if (__any(alpha < 1.f)) {
;                     if (hi == 0) al_l[r32] = alpha;
;                     asm volatile("s_waitcnt lgkmcnt(0)" ::: "memory");
;                     float ar[16];
; #pragma unroll
;                     for (int r = 0; r < 16; ++r) ar[r] = al_l[crow(r, hi)];
; #pragma unroll
;                     for (int d = 0; d < 8; ++d)
; #pragma unroll
;                         for (int r = 0; r < 16; ++r) o[d][r] *= ar[r];
;                 }
	s_and_saveexec_b64 s[80:81], s[8:9]
	ds_write_b32 v196, v227 offset:128
	s_or_b64 exec, exec, s[80:81]
	s_waitcnt lgkmcnt(0)
	ds_read_b128 v[152:155], v214 offset:224
	ds_read_b128 v[148:151], v214 offset:192
	ds_read_b128 v[144:147], v214 offset:160
	ds_read_b128 v[140:143], v214 offset:128
	s_waitcnt lgkmcnt(0)
	v_pk_mul_f32 v[126:127], v[126:127], v[152:153]
	v_pk_mul_f32 v[122:123], v[122:123], v[148:149]
	v_pk_mul_f32 v[118:119], v[118:119], v[144:145]
	v_pk_mul_f32 v[128:129], v[128:129], v[154:155]
	v_pk_mul_f32 v[124:125], v[124:125], v[150:151]
	v_pk_mul_f32 v[120:121], v[120:121], v[146:147]
	v_pk_mul_f32 v[116:117], v[116:117], v[142:143]
	v_pk_mul_f32 v[114:115], v[114:115], v[140:141]
	v_pk_mul_f32 v[110:111], v[110:111], v[152:153]
	v_pk_mul_f32 v[106:107], v[106:107], v[148:149]
	v_pk_mul_f32 v[102:103], v[102:103], v[144:145]
	v_pk_mul_f32 v[112:113], v[112:113], v[154:155]
	v_pk_mul_f32 v[108:109], v[108:109], v[150:151]
	v_pk_mul_f32 v[104:105], v[104:105], v[146:147]
	v_pk_mul_f32 v[100:101], v[100:101], v[142:143]
	v_pk_mul_f32 v[98:99], v[98:99], v[140:141]
	v_pk_mul_f32 v[94:95], v[94:95], v[152:153]
	v_pk_mul_f32 v[90:91], v[90:91], v[148:149]
	v_pk_mul_f32 v[86:87], v[86:87], v[144:145]
	v_pk_mul_f32 v[96:97], v[96:97], v[154:155]
	v_pk_mul_f32 v[92:93], v[92:93], v[150:151]
	v_pk_mul_f32 v[88:89], v[88:89], v[146:147]
	v_pk_mul_f32 v[84:85], v[84:85], v[142:143]
	v_pk_mul_f32 v[82:83], v[82:83], v[140:141]
	v_pk_mul_f32 v[78:79], v[78:79], v[152:153]
	v_pk_mul_f32 v[74:75], v[74:75], v[148:149]
	v_pk_mul_f32 v[70:71], v[70:71], v[144:145]
	v_pk_mul_f32 v[80:81], v[80:81], v[154:155]
	v_pk_mul_f32 v[76:77], v[76:77], v[150:151]
	v_pk_mul_f32 v[72:73], v[72:73], v[146:147]
	v_pk_mul_f32 v[68:69], v[68:69], v[142:143]
	v_pk_mul_f32 v[66:67], v[66:67], v[140:141]
	v_pk_mul_f32 v[62:63], v[62:63], v[152:153]
	v_pk_mul_f32 v[58:59], v[58:59], v[148:149]
	v_pk_mul_f32 v[54:55], v[54:55], v[144:145]
	v_pk_mul_f32 v[64:65], v[64:65], v[154:155]
	v_pk_mul_f32 v[60:61], v[60:61], v[150:151]
	v_pk_mul_f32 v[56:57], v[56:57], v[146:147]
	v_pk_mul_f32 v[52:53], v[52:53], v[142:143]
	v_pk_mul_f32 v[50:51], v[50:51], v[140:141]
	v_pk_mul_f32 v[46:47], v[46:47], v[152:153]
	v_pk_mul_f32 v[42:43], v[42:43], v[148:149]
	v_pk_mul_f32 v[38:39], v[38:39], v[144:145]
	v_pk_mul_f32 v[48:49], v[48:49], v[154:155]
	v_pk_mul_f32 v[44:45], v[44:45], v[150:151]
	v_pk_mul_f32 v[40:41], v[40:41], v[146:147]
	v_pk_mul_f32 v[36:37], v[36:37], v[142:143]
	v_pk_mul_f32 v[34:35], v[34:35], v[140:141]
	v_pk_mul_f32 v[30:31], v[30:31], v[152:153]
	v_pk_mul_f32 v[26:27], v[26:27], v[148:149]
	v_pk_mul_f32 v[22:23], v[22:23], v[144:145]
	v_pk_mul_f32 v[32:33], v[32:33], v[154:155]
	v_pk_mul_f32 v[28:29], v[28:29], v[150:151]
	v_pk_mul_f32 v[24:25], v[24:25], v[146:147]
	v_pk_mul_f32 v[20:21], v[20:21], v[142:143]
	v_pk_mul_f32 v[18:19], v[18:19], v[140:141]
	v_pk_mul_f32 v[14:15], v[14:15], v[152:153]
	v_pk_mul_f32 v[10:11], v[10:11], v[148:149]
	v_pk_mul_f32 v[6:7], v[6:7], v[144:145]
	v_pk_mul_f32 v[16:17], v[16:17], v[154:155]
	v_pk_mul_f32 v[12:13], v[12:13], v[150:151]
	v_pk_mul_f32 v[8:9], v[8:9], v[146:147]
	v_pk_mul_f32 v[4:5], v[4:5], v[142:143]
	v_pk_mul_f32 v[2:3], v[2:3], v[140:141]

; #define LAS __attribute__((address_space(3)))
; DI void attn_stage(const bf16_t* kbase, const bf16_t* vbase, unsigned koff, unsigned voff, LAS unsigned char* ldsbuf, int wid) {
; #pragma unroll
;     for (int i = 0; i < 2; ++i) {
;         const char* src = (const char*)kbase + (size_t)(i * 128) * 2;
;         __builtin_amdgcn_global_load_lds((const unsigned*)(src + koff), (LAS unsigned*)(ldsbuf + (wid + 8 * i) * 1024), 16, 0, 0);
;     }
; #pragma unroll
;     for (int i = 0; i < 2; ++i) {
;         const char* src = (const char*)vbase + (size_t)(16 * i * 2048) * 2;
;         __builtin_amdgcn_global_load_lds((const unsigned*)(src + voff), (LAS unsigned*)(ldsbuf + 16384 + (wid + 8 * i) * 1024), 16, 0, 0);
;     }
; }
; DI void phase_attn(int wid0, const Params& p, int L, unsigned char* lds, bool dry) {
;     ...
;             if (t + 1 < ntiles) attn_stage(kh_ + (size_t)(b * 4096 + 32 * t) * 2048, vh_ + (size_t)(b * 4096 + 32 * t) * 2048, koff, voff, ldsl + 65536 + ((t + 1) & 1) * 32768, wid);
;             const int kpos0 = (t == 0) ? 0 : 16 + 32 * (t - 1);
;             if (kpos0 <= wq0 + 31) {
.Lattn_skip0:
	s_add_i32 m0, s4, 0x8000
	s_nop 0
	global_load_lds_dwordx4 v131, s[88:89]
	s_add_i32 m0, s4, 0xa000
	s_nop 0
	global_load_lds_dwordx4 v131, s[90:91]
	v_add_u32_e32 v131, 0x20000, v131
	s_add_i32 m0, s96, 0x4000
	s_nop 0
	global_load_lds_dwordx4 v208, s[92:93]
	s_add_i32 m0, s96, 0x6000
	s_nop 0
	global_load_lds_dwordx4 v208, s[94:95]
	v_add_u32_e32 v208, 0x20000, v208
	s_bitcmp1_b32 s100, 8
	s_cbranch_scc0 .Lattn_latch0

; #define LAS __attribute__((address_space(3)))
; DI void attn_stage(const bf16_t* kbase, const bf16_t* vbase, unsigned koff, unsigned voff, LAS unsigned char* ldsbuf, int wid) {
; #pragma unroll
;     for (int i = 0; i < 2; ++i) {
;         const char* src = (const char*)kbase + (size_t)(i * 128) * 2;
;         __builtin_amdgcn_global_load_lds((const unsigned*)(src + koff), (LAS unsigned*)(ldsbuf + (wid + 8 * i) * 1024), 16, 0, 0);
;     }
; #pragma unroll
;     for (int i = 0; i < 2; ++i) {
;         const char* src = (const char*)vbase + (size_t)(16 * i * 2048) * 2;
;         __builtin_amdgcn_global_load_lds((const unsigned*)(src + voff), (LAS unsigned*)(ldsbuf + 16384 + (wid + 8 * i) * 1024), 16, 0, 0);
;     }
; }
; DI void phase_attn(int wid0, const Params& p, int L, unsigned char* lds, bool dry) {
;     ...
;             if (t + 1 < ntiles) attn_stage(kh_ + (size_t)(b * 4096 + 32 * t) * 2048, vh_ + (size_t)(b * 4096 + 32 * t) * 2048, koff, voff, ldsl + 65536 + ((t + 1) & 1) * 32768, wid);
;             const int kpos0 = (t == 0) ? 0 : 16 + 32 * (t - 1);
;             if (kpos0 <= wq0 + 31) {
.Lattn_skip1:
	s_add_i32 m0, s4, 0x0
	s_nop 0
	global_load_lds_dwordx4 v131, s[88:89]
	s_add_i32 m0, s4, 0x2000
	s_nop 0
	global_load_lds_dwordx4 v131, s[90:91]
	v_add_u32_e32 v131, 0x20000, v131
	s_add_i32 m0, s96, 0x8000
	s_nop 0
	global_load_lds_dwordx4 v208, s[92:93]
	s_add_i32 m0, s96, 0xa000
	s_nop 0
	global_load_lds_dwordx4 v208, s[94:95]
	v_add_u32_e32 v208, 0x20000, v208
	s_bitcmp1_b32 s100, 8
	s_cbranch_scc0 .Lattn_latch1

; #define LAS __attribute__((address_space(3)))
; DI void attn_stage(const bf16_t* kbase, const bf16_t* vbase, unsigned koff, unsigned voff, LAS unsigned char* ldsbuf, int wid) {
; #pragma unroll
;     for (int i = 0; i < 2; ++i) {
;         const char* src = (const char*)kbase + (size_t)(i * 128) * 2;
;         __builtin_amdgcn_global_load_lds((const unsigned*)(src + koff), (LAS unsigned*)(ldsbuf + (wid + 8 * i) * 1024), 16, 0, 0);
;     }
; #pragma unroll
;     for (int i = 0; i < 2; ++i) {
;         const char* src = (const char*)vbase + (size_t)(16 * i * 2048) * 2;
;         __builtin_amdgcn_global_load_lds((const unsigned*)(src + voff), (LAS unsigned*)(ldsbuf + 16384 + (wid + 8 * i) * 1024), 16, 0, 0);
;     }
; }
; DI void phase_attn(int wid0, const Params& p, int L, unsigned char* lds, bool dry) {
;     ...
;             if (t + 1 < ntiles) attn_stage(kh_ + (size_t)(b * 4096 + 32 * t) * 2048, vh_ + (size_t)(b * 4096 + 32 * t) * 2048, koff, voff, ldsl + 65536 + ((t + 1) & 1) * 32768, wid);
;             const int kpos0 = (t == 0) ? 0 : 16 + 32 * (t - 1);
;             if (kpos0 <= wq0 + 31) {
.Lattn_skip2:
	s_add_i32 m0, s4, 0x8000
	s_nop 0
	global_load_lds_dwordx4 v131, s[88:89]
	s_add_i32 m0, s4, 0xa000
	s_nop 0
	global_load_lds_dwordx4 v131, s[90:91]
	v_add_u32_e32 v131, 0x20000, v131
	s_add_i32 m0, s96, 0xc000
	s_nop 0
	global_load_lds_dwordx4 v208, s[92:93]
	s_add_i32 m0, s96, 0xe000
	s_nop 0
	global_load_lds_dwordx4 v208, s[94:95]
	v_add_u32_e32 v208, 0x20000, v208
	s_bitcmp1_b32 s100, 8
	s_cbranch_scc0 .Lattn_latch2

; #define LAS __attribute__((address_space(3)))
; DI void attn_stage(const bf16_t* kbase, const bf16_t* vbase, unsigned koff, unsigned voff, LAS unsigned char* ldsbuf, int wid) {
; #pragma unroll
;     for (int i = 0; i < 2; ++i) {
;         const char* src = (const char*)kbase + (size_t)(i * 128) * 2;
;         __builtin_amdgcn_global_load_lds((const unsigned*)(src + koff), (LAS unsigned*)(ldsbuf + (wid + 8 * i) * 1024), 16, 0, 0);
;     }
; #pragma unroll
;     for (int i = 0; i < 2; ++i) {
;         const char* src = (const char*)vbase + (size_t)(16 * i * 2048) * 2;
;         __builtin_amdgcn_global_load_lds((const unsigned*)(src + voff), (LAS unsigned*)(ldsbuf + 16384 + (wid + 8 * i) * 1024), 16, 0, 0);
;     }
; }
; DI void phase_attn(int wid0, const Params& p, int L, unsigned char* lds, bool dry) {
;     ...
;             if (t + 1 < ntiles) attn_stage(kh_ + (size_t)(b * 4096 + 32 * t) * 2048, vh_ + (size_t)(b * 4096 + 32 * t) * 2048, koff, voff, ldsl + 65536 + ((t + 1) & 1) * 32768, wid);
;             const int kpos0 = (t == 0) ? 0 : 16 + 32 * (t - 1);
;             if (kpos0 <= wq0 + 31) {
.Lattn_skip3:
	s_add_i32 m0, s4, 0x0
	s_nop 0
	global_load_lds_dwordx4 v131, s[88:89]
	s_add_i32 m0, s4, 0x2000
	s_nop 0
	global_load_lds_dwordx4 v131, s[90:91]
	v_add_u32_e32 v131, 0x20000, v131
	s_add_i32 m0, s96, 0x0
	s_nop 0
	global_load_lds_dwordx4 v208, s[92:93]
	s_add_i32 m0, s96, 0x2000
	s_nop 0
	global_load_lds_dwordx4 v208, s[94:95]
	v_add_u32_e32 v208, 0x20000, v208
	s_bitcmp1_b32 s100, 8
	s_cbranch_scc0 .Lattn_latch3
